# prep: half of the blocks run the transposes and x conversion before the fp4 table streaming and half after (overlap latency-bound items with bandwidth-bound streaming)
# baseline (speedup 1.0000x reference)
.LBB0_29:
	s_lshr_b32 s32, s2, 5
	s_xor_b32 s32, s32, s2
	s_bitcmp1_b32 s32, 3
	s_cbranch_scc1 .Lprep_rest

.Luv_done:
	s_lshr_b32 s32, s2, 5
	s_xor_b32 s32, s32, s2
	s_bitcmp1_b32 s32, 3
	s_cbranch_scc0 .Lprep_rest
	s_waitcnt vmcnt(0)
	s_branch .Lprep_end
